# P0: transpose items dealt starting from block 128 so the blocks with two adaLN items get the fewest transposes
# baseline (speedup 1.0000x reference)
.LBB0_28:
	s_lshl_b32 s2, s96, 3
	s_add_u32 s34, s50, 0x2380000
	s_addc_u32 s35, s51, 0
	s_add_u32 s0, s50, 0x2280000
	s_addc_u32 s1, s51, 0
	s_add_u32 s74, s50, 0x2200000
	v_writelane_b32 v254, s0, 34
	s_addc_u32 s75, s51, 0
	v_mov_b32_e32 v2, v250
	v_writelane_b32 v254, s1, 35
	s_add_u32 s0, s50, 0x2100000
	s_addc_u32 s1, s51, 0
	v_writelane_b32 v254, s0, 36
	s_waitcnt lgkmcnt(0)
	s_barrier
	v_writelane_b32 v254, s1, 37
	s_add_u32 s0, s50, 0x1900000
	s_addc_u32 s1, s51, 0
	v_writelane_b32 v254, s0, 38
	s_nop 1
	v_writelane_b32 v254, s1, 39
	s_lshl_b32 s0, s92, 3
	v_writelane_b32 v254, s0, 40
	v_ashrrev_i32_e32 v3, 6, v2
	v_add_u32_e32 v20, s2, v3
	s_cmpk_eq_u32 s92, 0x100
	s_cbranch_scc0 .Lp0_norot
	s_add_i32 s0, s96, 0x80
	s_and_b32 s0, s0, 0xff
	s_lshl_b32 s0, s0, 3
	v_add_u32_e32 v20, s0, v3
.Lp0_norot:
	v_writelane_b32 v254, s1, 41
	s_mov_b32 s0, s2
	v_writelane_b32 v254, s0, 42
	s_nop 1
	v_writelane_b32 v254, s1, 43
	s_movk_i32 s0, 0x11e0
	v_cmp_gt_i32_e32 vcc, s0, v20
	s_and_saveexec_b64 s[4:5], vcc
	s_cbranch_execz .LBB0_49
	v_bfe_u32 v22, v2, 3, 3
	v_lshlrev_b32_e32 v7, 2, v2
	v_or_b32_e32 v25, 8, v22
	v_bfe_u32 v21, v2, 4, 2
	v_and_b32_e32 v4, 60, v7
	v_lshlrev_b32_e32 v6, 3, v2
	v_and_b32_e32 v2, 32, v7
	v_lshrrev_b32_e32 v7, 1, v25
	v_or_b32_e32 v27, 16, v22
	v_or_b32_e32 v26, v7, v2
	v_lshrrev_b32_e32 v7, 1, v27
	v_or_b32_e32 v29, 24, v22
	v_or_b32_e32 v28, v7, v2
	v_lshrrev_b32_e32 v7, 1, v29
	v_or_b32_e32 v31, 32, v22
	s_movk_i32 s0, 0x4100
	v_or_b32_e32 v30, v7, v2
	v_lshrrev_b32_e32 v7, 1, v31
	v_or_b32_e32 v33, 40, v22
	v_mul_lo_u32 v3, v3, s0
	v_or_b32_e32 v32, v7, v2
	v_lshrrev_b32_e32 v7, 1, v33
	v_or_b32_e32 v35, 48, v22
	v_add_u32_e32 v5, 32, v3
	v_and_b32_e32 v6, 56, v6
	s_movk_i32 s0, 0x104
	v_or_b32_e32 v34, v7, v2
	v_lshrrev_b32_e32 v7, 1, v35
	v_or_b32_e32 v37, 56, v22
	v_lshl_add_u32 v8, v4, 2, v5
	v_mad_u32_u24 v23, v6, s0, v5
	v_mul_u32_u24_e32 v5, 0x104, v21
	v_or_b32_e32 v36, v7, v2
	v_lshrrev_b32_e32 v7, 1, v37
	v_mov_b32_e32 v3, 0
	v_or_b32_e32 v24, v2, v21
	v_or_b32_e32 v38, v7, v2
	s_mov_b64 s[6:7], 0
	v_lshlrev_b32_e32 v2, 2, v4
	v_add_u32_e32 v39, v8, v5
	v_lshlrev_b32_e32 v4, 1, v6
	s_branch .LBB0_32
